# v33 + grid barrier: the first workgroup of each XCD to arrive issues an early L2 write-back (one extra per XCD per barrier) so the last arriver's flush is short
# speedup vs baseline: 1.0166x; 1.0166x over previous
.LBB0_1060:
	s_or_b64 exec, exec, s[10:11]
	v_cvt_f32_u32_e32 v8, v6
	s_waitcnt vmcnt(0)
	v_readfirstlane_b32 s0, v7
	v_sub_u32_e32 v7, 0, v6
	v_rcp_iflag_f32_e32 v8, v8
	v_add_u32_e32 v9, s0, v5
	v_mul_f32_e32 v8, 0x4f7ffffe, v8
	v_cvt_u32_f32_e32 v8, v8
	v_mul_lo_u32 v5, v7, v8
	v_mul_hi_u32 v5, v8, v5
	v_add_u32_e32 v5, v8, v5
	v_mul_hi_u32 v5, v9, v5
	v_mul_lo_u32 v7, v5, v6
	v_sub_u32_e32 v7, v9, v7
	v_add_u32_e32 v8, 1, v5
	v_cmp_ge_u32_e32 vcc, v7, v6
	s_nop 1
	v_cndmask_b32_e32 v5, v5, v8, vcc
	v_sub_u32_e32 v8, v7, v6
	v_cndmask_b32_e32 v7, v7, v8, vcc
	v_add_u32_e32 v8, 1, v5
	v_cmp_ge_u32_e32 vcc, v7, v6
	v_add_u32_e32 v7, 1, v9
	s_nop 0
	v_cndmask_b32_e32 v5, v5, v8, vcc
	v_mul_lo_u32 v8, v6, v5
	v_cmp_eq_u32_e32 vcc, v9, v8
	s_cbranch_vccz .Lbw_skip
	buffer_wbl2 sc1
.Lbw_skip:
	v_add_u32_e32 v6, v8, v6
	v_cmp_ne_u32_e32 vcc, v7, v6
	s_and_saveexec_b64 s[0:1], vcc
	s_xor_b64 s[10:11], exec, s[0:1]
	s_cbranch_execz .LBB0_1074
	s_waitcnt lgkmcnt(0)
	global_load_dword v4, v232, s[8:9] offset:1024 sc1
	s_add_u32 s16, s8, 0x2400
	s_addc_u32 s17, s9, 0
	s_waitcnt vmcnt(0)
	v_cmp_eq_u32_e32 vcc, v4, v5
	s_and_saveexec_b64 s[12:13], vcc
	s_cbranch_execz .LBB0_1073
	s_add_u32 s14, s78, 0x1f885200
	s_addc_u32 s15, s79, 0
	s_mov_b32 s0, 1
	s_mov_b64 s[18:19], 0
	s_branch .LBB0_1064
